# P1: same-XCD workgroups pre-load the ada GEMM's B tiles into the XCD's L2 before their conversions (re-test now that P1 is GEMM-bound)
# speedup vs baseline: 1.0022x; 1.0022x over previous
; #define INP(k) karg_in(k)
; #define lane opq(lane_now())
; __global__ void __launch_bounds__(NTHR, 2) fwd_megakernel(Params P) {
;     ...
;     { pg8::Gemm g{(const bf16*)(ws + WS_CB), (const bf16*)(ws + WS_WADA), nullptr, nullptr, D}; pg8::StaticOrder S; S.init(256, NADA, G, wg);
;       EpiAda E{ADA, INP(9)}; pg8::gemm_phase(lds, g, S, E, wave);
;       if (wg >= 36) prologue<1>(P, lds, (wg - 36) * NWAVES + wave, (G - 36) * NWAVES, wave, lane); }
.Lcv_pre:
	s_cmp_eq_u32 s99, 0
	s_cbranch_scc0 .Lcv_nowarm
	s_and_b32 s4, s2, 7
	s_sub_i32 s5, s2, 36
	s_lshr_b32 s5, s5, 3
	s_mul_i32 s6, s4, 5
	s_lshl_b32 s7, s4, 2
	s_add_i32 s7, s7, 4
	s_movk_i32 s8, 10
	s_cmp_lt_u32 s4, 4
	s_cselect_b32 s6, s6, s7
	s_movk_i32 s7, 12
	s_cselect_b32 s7, s7, s8
	s_lshl_b32 s6, s6, 19
	s_mul_i32 s5, s5, s7
	s_lshl_b32 s5, s5, 13
	s_add_u32 s6, s6, s5
	s_add_u32 s6, s6, 0xc140000
	s_add_u32 s8, s76, s6
	s_addc_u32 s9, s77, 0
	v_lshlrev_b32_e32 v0, 4, v166
	s_lshl_b32 s10, s3, 10
	v_add_u32_e32 v0, s10, v0
.Lcv_warm_loop:
	global_load_dwordx4 v[252:255], v0, s[8:9]
	v_add_u32_e32 v0, 0x2000, v0
	s_sub_i32 s7, s7, 1
	s_cmp_lg_u32 s7, 0
	s_cbranch_scc1 .Lcv_warm_loop
